# dil staging pass unrolled over the 6 tiles with all 12 K/V tile loads issued up front into separate registers (rows clamped instead of masked) and counted vmcnt waits
# speedup vs baseline: 1.0112x; 1.0041x over previous
; #define LAS __attribute__((address_space(3)))
; template <int K> __device__ __forceinline__ float swz_f(float v) { return __uint_as_float(swz_u<K>(__float_as_uint(v))); }
; #define UNPACK8(v, k) const float k##0 = blo(v.x), k##1 = bhi(v.x), k##2 = blo(v.y), k##3 = bhi(v.y), k##4 = blo(v.z), k##5 = bhi(v.z), k##6 = blo(v.w), k##7 = bhi(v.w)
; __device__ __forceinline__ unsigned cvtpk(float lo, float hi) { f32x2_t v = {lo, hi}; bf16x2_t b = __builtin_convertvector(v, bf16x2_t); return __builtin_bit_cast(unsigned, b); }
; __device__ __forceinline__ void kv_fetch(const KVSrc& s, int tid, u32x4& kc, u32x4& vc) {
;     const int kl = tid >> 3, ch = tid & 7, i = s.first + kl;
;     if (i >= s.lo && i < s.hi) { kc = *(const u32x4*)(s.k + (long)i * s.pitch + 8 * ch); vc = *(const u32x4*)(s.v + (long)i * s.pitch + 8 * ch); }
;     else { kc = (u32x4){0u, 0u, 0u, 0u}; vc = kc; }
; }
; template <bool NORM> __device__ __forceinline__ void kv_store(u32x4 kc, u32x4 vc, const float (&g)[8], LAS unsigned char* ksb, LAS unsigned char* vtb, int tid) {
;     const int kl = tid >> 3, ch = tid & 7;
;     if (NORM) { UNPACK8(kc, k); float ss = (k0 * k0 + k1 * k1) + (k2 * k2 + k3 * k3) + (k4 * k4 + k5 * k5) + (k6 * k6 + k7 * k7);
;         ss += swz_f<1>(ss); ss += swz_f<2>(ss); ss += swz_f<4>(ss);
;         const float rs = rsqrtf(ss * (1.f / 64.f) + EPS);
;         kc.x = cvtpk(k0 * rs * g[0], k1 * rs * g[1]); kc.y = cvtpk(k2 * rs * g[2], k3 * rs * g[3]); kc.z = cvtpk(k4 * rs * g[4], k5 * rs * g[5]); kc.w = cvtpk(k6 * rs * g[6], k7 * rs * g[7]); }
;     *(LAS u32x4*)(ksb + kl * KSB + ch * 16) = kc;
;     LAS unsigned short* vp = (LAS unsigned short*)(vtb + (8 * ch) * VTB + kl * 2);
;     vp[0 * (VTB / 2)] = (unsigned short)(vc.x & 0xffffu); vp[1 * (VTB / 2)] = (unsigned short)(vc.x >> 16);
;     vp[2 * (VTB / 2)] = (unsigned short)(vc.y & 0xffffu); vp[3 * (VTB / 2)] = (unsigned short)(vc.y >> 16);
;     vp[4 * (VTB / 2)] = (unsigned short)(vc.z & 0xffffu); vp[5 * (VTB / 2)] = (unsigned short)(vc.z >> 16);
;     vp[6 * (VTB / 2)] = (unsigned short)(vc.w & 0xffffu); vp[7 * (VTB / 2)] = (unsigned short)(vc.w >> 16);
.LBB0_863:
	s_add_i32 s101, s30, -1
	s_add_i32 s0, s43, 0
	v_add_u32_e32 v185, s0, v114
	v_min_i32_e32 v185, s101, v185
	v_mad_u64_u32 v[64:65], s[26:27], s44, v185, 0
	v_lshlrev_b64 v[64:65], 1, v[64:65]
	v_lshl_add_u64 v[66:67], v[102:103], 0, v[64:65]
	v_lshl_add_u64 v[68:69], v[104:105], 0, v[64:65]
	global_load_dwordx4 v[64:67], v[66:67], off
	s_nop 0
	global_load_dwordx4 v[68:71], v[68:69], off
	s_add_i32 s0, s43, 64
	v_add_u32_e32 v185, s0, v114
	v_min_i32_e32 v185, s101, v185
	v_mad_u64_u32 v[72:73], s[26:27], s44, v185, 0
	v_lshlrev_b64 v[72:73], 1, v[72:73]
	v_lshl_add_u64 v[74:75], v[102:103], 0, v[72:73]
	v_lshl_add_u64 v[76:77], v[104:105], 0, v[72:73]
	global_load_dwordx4 v[72:75], v[74:75], off
	s_nop 0
	global_load_dwordx4 v[76:79], v[76:77], off
	s_add_i32 s0, s43, 128
	v_add_u32_e32 v185, s0, v114
	v_min_i32_e32 v185, s101, v185
	v_mad_u64_u32 v[190:191], s[26:27], s44, v185, 0
	v_lshlrev_b64 v[190:191], 1, v[190:191]
	v_lshl_add_u64 v[192:193], v[102:103], 0, v[190:191]
	v_lshl_add_u64 v[194:195], v[104:105], 0, v[190:191]
	global_load_dwordx4 v[190:193], v[192:193], off
	s_nop 0
	global_load_dwordx4 v[194:197], v[194:195], off
	s_add_i32 s0, s43, 192
	v_add_u32_e32 v185, s0, v114
	v_min_i32_e32 v185, s101, v185
	v_mad_u64_u32 v[198:199], s[26:27], s44, v185, 0
	v_lshlrev_b64 v[198:199], 1, v[198:199]
	v_lshl_add_u64 v[200:201], v[102:103], 0, v[198:199]
	v_lshl_add_u64 v[202:203], v[104:105], 0, v[198:199]
	global_load_dwordx4 v[198:201], v[200:201], off
	s_nop 0
	global_load_dwordx4 v[202:205], v[202:203], off
	s_add_i32 s0, s43, 256
	v_add_u32_e32 v185, s0, v114
	v_min_i32_e32 v185, s101, v185
	v_mad_u64_u32 v[116:117], s[26:27], s44, v185, 0
	v_lshlrev_b64 v[116:117], 1, v[116:117]
	v_lshl_add_u64 v[118:119], v[102:103], 0, v[116:117]
	v_lshl_add_u64 v[120:121], v[104:105], 0, v[116:117]
	global_load_dwordx4 v[116:119], v[118:119], off
	s_nop 0
	global_load_dwordx4 v[120:123], v[120:121], off
	s_waitcnt vmcnt(11)
	v_and_b32_e32 v53, 0xffff0000, v5
	v_and_b32_e32 v51, 0xffff0000, v4
	v_lshlrev_b32_e32 v52, 16, v5
	v_lshlrev_b32_e32 v50, 16, v4
	v_pk_mul_f32 v[48:49], v[50:51], v[50:51]
	v_and_b32_e32 v57, 0xffff0000, v2
	v_and_b32_e32 v55, 0xffff0000, v3
	v_lshlrev_b32_e32 v54, 16, v3
	v_lshlrev_b32_e32 v56, 16, v2
	v_pk_fma_f32 v[48:49], v[52:53], v[52:53], v[48:49]
	s_mul_i32 s0, s6, 0x2400
	s_mul_i32 s98, s6, 0x3000
	s_add_i32 s98, s98, 0x9000
	s_add_i32 s16, s0, 0
	v_pk_fma_f32 v[48:49], v[54:55], v[54:55], v[48:49]
	v_pk_fma_f32 v[48:49], v[56:57], v[56:57], v[48:49]
	v_add_f32_e32 v48, v48, v49
	s_lshl_b32 s0, s6, 9
	s_sub_i32 s9, s16, s0
	s_cmp_ge_u32 s13, s24
	s_cselect_b64 s[4:5], -1, 0
	s_nop 1
	v_add_f32_dpp v48, v48, v48 quad_perm:[1,0,3,2] row_mask:0xf bank_mask:0xf
	s_nop 1
	v_add_f32_dpp v48, v48, v48 quad_perm:[2,3,0,1] row_mask:0xf bank_mask:0xf
	s_nop 1
	v_add_f32_dpp v48, v48, v48 row_half_mirror row_mask:0xf bank_mask:0xf
	v_fmamk_f32 v48, v48, 0x3c800000, v139
	v_rsq_f32_e32 v58, v48
	s_nop 0
	v_pk_mul_f32 v[48:49], v[58:59], v[56:57] op_sel_hi:[0,1]
	v_pk_mul_f32 v[54:55], v[58:59], v[54:55] op_sel_hi:[0,1]
	v_pk_mul_f32 v[50:51], v[58:59], v[50:51] op_sel_hi:[0,1]
	v_pk_mul_f32 v[52:53], v[58:59], v[52:53] op_sel_hi:[0,1]
	v_pk_mul_f32 v[48:49], v[14:15], v[48:49]
	v_pk_mul_f32 v[54:55], v[96:97], v[54:55]
	v_pk_mul_f32 v[50:51], v[98:99], v[50:51]
	v_pk_mul_f32 v[52:53], v[100:101], v[52:53]
	v_cvt_pk_bf16_f32 v48, v48, v49
	v_cvt_pk_bf16_f32 v49, v54, v55
	v_cvt_pk_bf16_f32 v50, v50, v51
	v_cvt_pk_bf16_f32 v51, v52, v53
	v_add3_u32 v52, s16, v95, v108
	ds_write_b128 v52, v[48:51]
	v_add_u32_e32 v48, s98, v110
	s_and_b64 vcc, exec, s[4:5]
	s_waitcnt vmcnt(10)
	ds_write_b128 v48, v[6:9] offset:18432
	s_add_i32 s6, s6, 1
	s_waitcnt vmcnt(9)
	v_and_b32_e32 v53, 0xffff0000, v67
	v_and_b32_e32 v51, 0xffff0000, v66
	v_lshlrev_b32_e32 v52, 16, v67
	v_lshlrev_b32_e32 v50, 16, v66
	v_pk_mul_f32 v[48:49], v[50:51], v[50:51]
	v_and_b32_e32 v57, 0xffff0000, v64
	v_and_b32_e32 v55, 0xffff0000, v65
	v_lshlrev_b32_e32 v54, 16, v65
	v_lshlrev_b32_e32 v56, 16, v64
	v_pk_fma_f32 v[48:49], v[52:53], v[52:53], v[48:49]
	s_mul_i32 s0, s6, 0x2400
	s_mul_i32 s98, s6, 0x3000
	s_add_i32 s98, s98, 0x9000
	s_add_i32 s16, s0, 0
	v_pk_fma_f32 v[48:49], v[54:55], v[54:55], v[48:49]
	v_pk_fma_f32 v[48:49], v[56:57], v[56:57], v[48:49]
	v_add_f32_e32 v48, v48, v49
	s_lshl_b32 s0, s6, 9
	s_sub_i32 s9, s16, s0
	s_cmp_ge_u32 s13, s24
	s_cselect_b64 s[4:5], -1, 0
	s_nop 1
	v_add_f32_dpp v48, v48, v48 quad_perm:[1,0,3,2] row_mask:0xf bank_mask:0xf
	s_nop 1
	v_add_f32_dpp v48, v48, v48 quad_perm:[2,3,0,1] row_mask:0xf bank_mask:0xf
	s_nop 1
	v_add_f32_dpp v48, v48, v48 row_half_mirror row_mask:0xf bank_mask:0xf
	v_fmamk_f32 v48, v48, 0x3c800000, v139
	v_rsq_f32_e32 v58, v48
	s_nop 0
	v_pk_mul_f32 v[48:49], v[58:59], v[56:57] op_sel_hi:[0,1]
	v_pk_mul_f32 v[54:55], v[58:59], v[54:55] op_sel_hi:[0,1]
	v_pk_mul_f32 v[50:51], v[58:59], v[50:51] op_sel_hi:[0,1]
	v_pk_mul_f32 v[52:53], v[58:59], v[52:53] op_sel_hi:[0,1]
	v_pk_mul_f32 v[48:49], v[14:15], v[48:49]
	v_pk_mul_f32 v[54:55], v[96:97], v[54:55]
	v_pk_mul_f32 v[50:51], v[98:99], v[50:51]
	v_pk_mul_f32 v[52:53], v[100:101], v[52:53]
	v_cvt_pk_bf16_f32 v48, v48, v49
	v_cvt_pk_bf16_f32 v49, v54, v55
	v_cvt_pk_bf16_f32 v50, v50, v51
	v_cvt_pk_bf16_f32 v51, v52, v53
	v_add3_u32 v52, s16, v95, v108
	ds_write_b128 v52, v[48:51]
	v_add_u32_e32 v48, s98, v110
	s_and_b64 vcc, exec, s[4:5]
	s_waitcnt vmcnt(8)
	ds_write_b128 v48, v[68:71] offset:18432
	s_add_i32 s6, s6, 1
	s_waitcnt vmcnt(7)
; #define LAS __attribute__((address_space(3)))
; template <int K> __device__ __forceinline__ float swz_f(float v) { return __uint_as_float(swz_u<K>(__float_as_uint(v))); }
; #define UNPACK8(v, k) const float k##0 = blo(v.x), k##1 = bhi(v.x), k##2 = blo(v.y), k##3 = bhi(v.y), k##4 = blo(v.z), k##5 = bhi(v.z), k##6 = blo(v.w), k##7 = bhi(v.w)
; __device__ __forceinline__ unsigned cvtpk(float lo, float hi) { f32x2_t v = {lo, hi}; bf16x2_t b = __builtin_convertvector(v, bf16x2_t); return __builtin_bit_cast(unsigned, b); }
; template <bool NORM> __device__ __forceinline__ void kv_store(u32x4 kc, u32x4 vc, const float (&g)[8], LAS unsigned char* ksb, LAS unsigned char* vtb, int tid) {
;     const int kl = tid >> 3, ch = tid & 7;
;     if (NORM) { UNPACK8(kc, k); float ss = (k0 * k0 + k1 * k1) + (k2 * k2 + k3 * k3) + (k4 * k4 + k5 * k5) + (k6 * k6 + k7 * k7);
;         ss += swz_f<1>(ss); ss += swz_f<2>(ss); ss += swz_f<4>(ss);
;         const float rs = rsqrtf(ss * (1.f / 64.f) + EPS);
;         kc.x = cvtpk(k0 * rs * g[0], k1 * rs * g[1]); kc.y = cvtpk(k2 * rs * g[2], k3 * rs * g[3]); kc.z = cvtpk(k4 * rs * g[4], k5 * rs * g[5]); kc.w = cvtpk(k6 * rs * g[6], k7 * rs * g[7]); }
;     *(LAS u32x4*)(ksb + kl * KSB + ch * 16) = kc;
;     LAS unsigned short* vp = (LAS unsigned short*)(vtb + (8 * ch) * VTB + kl * 2);
;     vp[0 * (VTB / 2)] = (unsigned short)(vc.x & 0xffffu); vp[1 * (VTB / 2)] = (unsigned short)(vc.x >> 16);
;     vp[2 * (VTB / 2)] = (unsigned short)(vc.y & 0xffffu); vp[3 * (VTB / 2)] = (unsigned short)(vc.y >> 16);
;     vp[4 * (VTB / 2)] = (unsigned short)(vc.z & 0xffffu); vp[5 * (VTB / 2)] = (unsigned short)(vc.z >> 16);
;     vp[6 * (VTB / 2)] = (unsigned short)(vc.w & 0xffffu); vp[7 * (VTB / 2)] = (unsigned short)(vc.w >> 16);
	v_and_b32_e32 v53, 0xffff0000, v75
	v_and_b32_e32 v51, 0xffff0000, v74
	v_lshlrev_b32_e32 v52, 16, v75
	v_lshlrev_b32_e32 v50, 16, v74
	v_pk_mul_f32 v[48:49], v[50:51], v[50:51]
	v_and_b32_e32 v57, 0xffff0000, v72
	v_and_b32_e32 v55, 0xffff0000, v73
	v_lshlrev_b32_e32 v54, 16, v73
	v_lshlrev_b32_e32 v56, 16, v72
	v_pk_fma_f32 v[48:49], v[52:53], v[52:53], v[48:49]
	s_mul_i32 s0, s6, 0x2400
	s_mul_i32 s98, s6, 0x3000
	s_add_i32 s98, s98, 0x9000
	s_add_i32 s16, s0, 0
	v_pk_fma_f32 v[48:49], v[54:55], v[54:55], v[48:49]
	v_pk_fma_f32 v[48:49], v[56:57], v[56:57], v[48:49]
	v_add_f32_e32 v48, v48, v49
	s_lshl_b32 s0, s6, 9
	s_sub_i32 s9, s16, s0
	s_cmp_ge_u32 s13, s24
	s_cselect_b64 s[4:5], -1, 0
	s_nop 1
	v_add_f32_dpp v48, v48, v48 quad_perm:[1,0,3,2] row_mask:0xf bank_mask:0xf
	s_nop 1
	v_add_f32_dpp v48, v48, v48 quad_perm:[2,3,0,1] row_mask:0xf bank_mask:0xf
	s_nop 1
	v_add_f32_dpp v48, v48, v48 row_half_mirror row_mask:0xf bank_mask:0xf
	v_fmamk_f32 v48, v48, 0x3c800000, v139
	v_rsq_f32_e32 v58, v48
	s_nop 0
	v_pk_mul_f32 v[48:49], v[58:59], v[56:57] op_sel_hi:[0,1]
	v_pk_mul_f32 v[54:55], v[58:59], v[54:55] op_sel_hi:[0,1]
	v_pk_mul_f32 v[50:51], v[58:59], v[50:51] op_sel_hi:[0,1]
	v_pk_mul_f32 v[52:53], v[58:59], v[52:53] op_sel_hi:[0,1]
	v_pk_mul_f32 v[48:49], v[14:15], v[48:49]
	v_pk_mul_f32 v[54:55], v[96:97], v[54:55]
	v_pk_mul_f32 v[50:51], v[98:99], v[50:51]
	v_pk_mul_f32 v[52:53], v[100:101], v[52:53]
	v_cvt_pk_bf16_f32 v48, v48, v49
	v_cvt_pk_bf16_f32 v49, v54, v55
	v_cvt_pk_bf16_f32 v50, v50, v51
	v_cvt_pk_bf16_f32 v51, v52, v53
	v_add3_u32 v52, s16, v95, v108
	ds_write_b128 v52, v[48:51]
	v_add_u32_e32 v48, s98, v110
	s_and_b64 vcc, exec, s[4:5]
	s_waitcnt vmcnt(6)
	ds_write_b128 v48, v[76:79] offset:18432
	s_add_i32 s6, s6, 1
	s_waitcnt vmcnt(5)
	v_and_b32_e32 v53, 0xffff0000, v193
	v_and_b32_e32 v51, 0xffff0000, v192
	v_lshlrev_b32_e32 v52, 16, v193
	v_lshlrev_b32_e32 v50, 16, v192
	v_pk_mul_f32 v[48:49], v[50:51], v[50:51]
	v_and_b32_e32 v57, 0xffff0000, v190
	v_and_b32_e32 v55, 0xffff0000, v191
	v_lshlrev_b32_e32 v54, 16, v191
	v_lshlrev_b32_e32 v56, 16, v190
	v_pk_fma_f32 v[48:49], v[52:53], v[52:53], v[48:49]
	s_mul_i32 s0, s6, 0x2400
	s_mul_i32 s98, s6, 0x3000
	s_add_i32 s98, s98, 0x9000
	s_add_i32 s16, s0, 0
	v_pk_fma_f32 v[48:49], v[54:55], v[54:55], v[48:49]
	v_pk_fma_f32 v[48:49], v[56:57], v[56:57], v[48:49]
	v_add_f32_e32 v48, v48, v49
	s_lshl_b32 s0, s6, 9
	s_sub_i32 s9, s16, s0
	s_cmp_ge_u32 s13, s24
	s_cselect_b64 s[4:5], -1, 0
	s_nop 1
	v_add_f32_dpp v48, v48, v48 quad_perm:[1,0,3,2] row_mask:0xf bank_mask:0xf
	s_nop 1
	v_add_f32_dpp v48, v48, v48 quad_perm:[2,3,0,1] row_mask:0xf bank_mask:0xf
	s_nop 1
	v_add_f32_dpp v48, v48, v48 row_half_mirror row_mask:0xf bank_mask:0xf
	v_fmamk_f32 v48, v48, 0x3c800000, v139
	v_rsq_f32_e32 v58, v48
	s_nop 0
	v_pk_mul_f32 v[48:49], v[58:59], v[56:57] op_sel_hi:[0,1]
	v_pk_mul_f32 v[54:55], v[58:59], v[54:55] op_sel_hi:[0,1]
	v_pk_mul_f32 v[50:51], v[58:59], v[50:51] op_sel_hi:[0,1]
	v_pk_mul_f32 v[52:53], v[58:59], v[52:53] op_sel_hi:[0,1]
	v_pk_mul_f32 v[48:49], v[14:15], v[48:49]
	v_pk_mul_f32 v[54:55], v[96:97], v[54:55]
	v_pk_mul_f32 v[50:51], v[98:99], v[50:51]
	v_pk_mul_f32 v[52:53], v[100:101], v[52:53]
	v_cvt_pk_bf16_f32 v48, v48, v49
	v_cvt_pk_bf16_f32 v49, v54, v55
	v_cvt_pk_bf16_f32 v50, v50, v51
	v_cvt_pk_bf16_f32 v51, v52, v53
	v_add3_u32 v52, s16, v95, v108
	ds_write_b128 v52, v[48:51]
	v_add_u32_e32 v48, s98, v110
	s_and_b64 vcc, exec, s[4:5]
	s_waitcnt vmcnt(4)
	ds_write_b128 v48, v[194:197] offset:18432
	s_add_i32 s6, s6, 1
	s_waitcnt vmcnt(3)
; #define LAS __attribute__((address_space(3)))
; template <int K> __device__ __forceinline__ float swz_f(float v) { return __uint_as_float(swz_u<K>(__float_as_uint(v))); }
; #define UNPACK8(v, k) const float k##0 = blo(v.x), k##1 = bhi(v.x), k##2 = blo(v.y), k##3 = bhi(v.y), k##4 = blo(v.z), k##5 = bhi(v.z), k##6 = blo(v.w), k##7 = bhi(v.w)
; __device__ __forceinline__ unsigned cvtpk(float lo, float hi) { f32x2_t v = {lo, hi}; bf16x2_t b = __builtin_convertvector(v, bf16x2_t); return __builtin_bit_cast(unsigned, b); }
; template <bool NORM> __device__ __forceinline__ void kv_store(u32x4 kc, u32x4 vc, const float (&g)[8], LAS unsigned char* ksb, LAS unsigned char* vtb, int tid) {
;     const int kl = tid >> 3, ch = tid & 7;
;     if (NORM) { UNPACK8(kc, k); float ss = (k0 * k0 + k1 * k1) + (k2 * k2 + k3 * k3) + (k4 * k4 + k5 * k5) + (k6 * k6 + k7 * k7);
;         ss += swz_f<1>(ss); ss += swz_f<2>(ss); ss += swz_f<4>(ss);
;         const float rs = rsqrtf(ss * (1.f / 64.f) + EPS);
;         kc.x = cvtpk(k0 * rs * g[0], k1 * rs * g[1]); kc.y = cvtpk(k2 * rs * g[2], k3 * rs * g[3]); kc.z = cvtpk(k4 * rs * g[4], k5 * rs * g[5]); kc.w = cvtpk(k6 * rs * g[6], k7 * rs * g[7]); }
;     *(LAS u32x4*)(ksb + kl * KSB + ch * 16) = kc;
;     LAS unsigned short* vp = (LAS unsigned short*)(vtb + (8 * ch) * VTB + kl * 2);
;     vp[0 * (VTB / 2)] = (unsigned short)(vc.x & 0xffffu); vp[1 * (VTB / 2)] = (unsigned short)(vc.x >> 16);
;     vp[2 * (VTB / 2)] = (unsigned short)(vc.y & 0xffffu); vp[3 * (VTB / 2)] = (unsigned short)(vc.y >> 16);
;     vp[4 * (VTB / 2)] = (unsigned short)(vc.z & 0xffffu); vp[5 * (VTB / 2)] = (unsigned short)(vc.z >> 16);
;     vp[6 * (VTB / 2)] = (unsigned short)(vc.w & 0xffffu); vp[7 * (VTB / 2)] = (unsigned short)(vc.w >> 16);
	v_and_b32_e32 v53, 0xffff0000, v201
	v_and_b32_e32 v51, 0xffff0000, v200
	v_lshlrev_b32_e32 v52, 16, v201
	v_lshlrev_b32_e32 v50, 16, v200
	v_pk_mul_f32 v[48:49], v[50:51], v[50:51]
	v_and_b32_e32 v57, 0xffff0000, v198
	v_and_b32_e32 v55, 0xffff0000, v199
	v_lshlrev_b32_e32 v54, 16, v199
	v_lshlrev_b32_e32 v56, 16, v198
	v_pk_fma_f32 v[48:49], v[52:53], v[52:53], v[48:49]
	s_mul_i32 s0, s6, 0x2400
	s_mul_i32 s98, s6, 0x3000
	s_add_i32 s98, s98, 0x9000
	s_add_i32 s16, s0, 0
	v_pk_fma_f32 v[48:49], v[54:55], v[54:55], v[48:49]
	v_pk_fma_f32 v[48:49], v[56:57], v[56:57], v[48:49]
	v_add_f32_e32 v48, v48, v49
	s_lshl_b32 s0, s6, 9
	s_sub_i32 s9, s16, s0
	s_cmp_ge_u32 s13, s24
	s_cselect_b64 s[4:5], -1, 0
	s_nop 1
	v_add_f32_dpp v48, v48, v48 quad_perm:[1,0,3,2] row_mask:0xf bank_mask:0xf
	s_nop 1
	v_add_f32_dpp v48, v48, v48 quad_perm:[2,3,0,1] row_mask:0xf bank_mask:0xf
	s_nop 1
	v_add_f32_dpp v48, v48, v48 row_half_mirror row_mask:0xf bank_mask:0xf
	v_fmamk_f32 v48, v48, 0x3c800000, v139
	v_rsq_f32_e32 v58, v48
	s_nop 0
	v_pk_mul_f32 v[48:49], v[58:59], v[56:57] op_sel_hi:[0,1]
	v_pk_mul_f32 v[54:55], v[58:59], v[54:55] op_sel_hi:[0,1]
	v_pk_mul_f32 v[50:51], v[58:59], v[50:51] op_sel_hi:[0,1]
	v_pk_mul_f32 v[52:53], v[58:59], v[52:53] op_sel_hi:[0,1]
	v_pk_mul_f32 v[48:49], v[14:15], v[48:49]
	v_pk_mul_f32 v[54:55], v[96:97], v[54:55]
	v_pk_mul_f32 v[50:51], v[98:99], v[50:51]
	v_pk_mul_f32 v[52:53], v[100:101], v[52:53]
	v_cvt_pk_bf16_f32 v48, v48, v49
	v_cvt_pk_bf16_f32 v49, v54, v55
	v_cvt_pk_bf16_f32 v50, v50, v51
	v_cvt_pk_bf16_f32 v51, v52, v53
	v_add3_u32 v52, s16, v95, v108
	ds_write_b128 v52, v[48:51]
	v_add_u32_e32 v48, s98, v110
	s_and_b64 vcc, exec, s[4:5]
	s_waitcnt vmcnt(2)
	ds_write_b128 v48, v[202:205] offset:18432
	s_add_i32 s6, s6, 1
	s_waitcnt vmcnt(1)
	v_and_b32_e32 v53, 0xffff0000, v119
	v_and_b32_e32 v51, 0xffff0000, v118
	v_lshlrev_b32_e32 v52, 16, v119
	v_lshlrev_b32_e32 v50, 16, v118
	v_pk_mul_f32 v[48:49], v[50:51], v[50:51]
	v_and_b32_e32 v57, 0xffff0000, v116
	v_and_b32_e32 v55, 0xffff0000, v117
	v_lshlrev_b32_e32 v54, 16, v117
	v_lshlrev_b32_e32 v56, 16, v116
	v_pk_fma_f32 v[48:49], v[52:53], v[52:53], v[48:49]
	s_mul_i32 s0, s6, 0x2400
	s_mul_i32 s98, s6, 0x3000
	s_add_i32 s98, s98, 0x9000
	s_add_i32 s16, s0, 0
	v_pk_fma_f32 v[48:49], v[54:55], v[54:55], v[48:49]
	v_pk_fma_f32 v[48:49], v[56:57], v[56:57], v[48:49]
	v_add_f32_e32 v48, v48, v49
	s_lshl_b32 s0, s6, 9
	s_sub_i32 s9, s16, s0
	s_cmp_ge_u32 s13, s24
	s_cselect_b64 s[4:5], -1, 0
	s_nop 1
	v_add_f32_dpp v48, v48, v48 quad_perm:[1,0,3,2] row_mask:0xf bank_mask:0xf
	s_nop 1
	v_add_f32_dpp v48, v48, v48 quad_perm:[2,3,0,1] row_mask:0xf bank_mask:0xf
	s_nop 1
	v_add_f32_dpp v48, v48, v48 row_half_mirror row_mask:0xf bank_mask:0xf
	v_fmamk_f32 v48, v48, 0x3c800000, v139
	v_rsq_f32_e32 v58, v48
	s_nop 0
	v_pk_mul_f32 v[48:49], v[58:59], v[56:57] op_sel_hi:[0,1]
	v_pk_mul_f32 v[54:55], v[58:59], v[54:55] op_sel_hi:[0,1]
	v_pk_mul_f32 v[50:51], v[58:59], v[50:51] op_sel_hi:[0,1]
	v_pk_mul_f32 v[52:53], v[58:59], v[52:53] op_sel_hi:[0,1]
	v_pk_mul_f32 v[48:49], v[14:15], v[48:49]
	v_pk_mul_f32 v[54:55], v[96:97], v[54:55]
	v_pk_mul_f32 v[50:51], v[98:99], v[50:51]
	v_pk_mul_f32 v[52:53], v[100:101], v[52:53]
	v_cvt_pk_bf16_f32 v48, v48, v49
	v_cvt_pk_bf16_f32 v49, v54, v55
	v_cvt_pk_bf16_f32 v50, v50, v51
	v_cvt_pk_bf16_f32 v51, v52, v53
	v_add3_u32 v52, s16, v95, v108
	ds_write_b128 v52, v[48:51]
	v_add_u32_e32 v48, s98, v110
	s_and_b64 vcc, exec, s[4:5]
	s_waitcnt vmcnt(0)
	ds_write_b128 v48, v[120:123] offset:18432
